# scan prefetch + lazy softmax rescale (T=8) in NSA window/selected loops
# speedup vs baseline: 1.0019x; 1.0019x over previous
; #define LAS __attribute__((address_space(3)))
; __device__ __forceinline__ f32x16 mfma32(bf16x8 a, bf16x8 b, f32x16 c) { return __builtin_amdgcn_mfma_f32_32x32x16_bf16(a, b, c, 0, 0, 0); }
; template <int MODE> ...
;     ...
;     { const LAS unsigned char* kp = lds + NSA_KB + bufn * 16384 + lane * 16;
; #pragma unroll
;       for (int kt = 0; kt < 2; ++kt) { sn[kt] = zero16();
; #pragma unroll
;           for (int ks = 0; ks < 8; ++ks) sn[kt] = mfma32(*(const LAS bf16x8*)(kp + kt * 8192 + ks * 1024), qf[ks], sn[kt]); } }
;     if (MODE == 1) {
; #pragma unroll
;         for (int kt = 0; kt < 2; ++kt)
; #pragma unroll
;             for (int r = 0; r < 16; ++r) s[kt][r] = (s[kt][r] > -1e29f) ? __builtin_amdgcn_exp2f(s[kt][r] - m_fin) * invl : 0.f;
;         LAS float* impa = (LAS float*)(lds + NSA_IMPA) + w * 8 * 66;
;         LAS float* impb = (LAS float*)(lds + NSA_IMPB) + w * 8 * 66;
; #pragma unroll
;         for (int kt = 0; kt < 2; ++kt)
; #pragma unroll
;             for (int q = 0; q < 4; ++q) {
;                 float A_ = s[kt][4 * q] + s[kt][4 * q + 1] + s[kt][4 * q + 2] + 0.5f * s[kt][4 * q + 3], B_ = 0.5f * s[kt][4 * q + 3];
;                 A_ += __shfl_xor(A_, 1); A_ += __shfl_xor(A_, 2); B_ += __shfl_xor(B_, 1); B_ += __shfl_xor(B_, 2);
;                 const int j = 8 * (2 * idx + kt) + 2 * q + hi;
;                 if (hd == 0) { impa[tl * 66 + j] = A_; impb[tl * 66 + j + 1] = B_; }
;             }
;     } else {
;         float tm = -3.0e38f;
; #pragma unroll
;         for (int kt = 0; kt < 2; ++kt)
; #pragma unroll
;             for (int r = 0; r < 16; r += 2) tm = fmaxf(fmaxf(tm, s[kt][r]), s[kt][r + 1]);
;         tm = tm * cs + offl;
;         tm = max_xor32(tm);
;         const float mn = fmaxf(mrun, tm), al = __builtin_amdgcn_exp2f(mrun - mn); float ps = 0.f;
;         const float om = offl - mn;
; #pragma unroll
;         for (int kt = 0; kt < 2; ++kt)
; #pragma unroll
;             for (int r = 0; r < 16; ++r) { const float p = __builtin_amdgcn_exp2f(s[kt][r] * cs + om); s[kt][r] = p; ps += p; }
;         lrun = lrun * al + ps; mrun = mn;
;         if (MODE != 0) {
;             if (__builtin_amdgcn_ballot_w64(al != 1.0f)) {
; #pragma unroll
;                 for (int dt = 0; dt < 4; ++dt) O[dt] = O[dt] * al;
;             }
;         }
.LBB0_1219:
	s_lshl_b32 s7, s13, 14
	s_add_i32 s7, s7, 0
	v_lshlrev_b32_e32 v171, 4, v64
	v_add_u32_e32 v64, s7, v171
	ds_read_b128 v[0:3], v64
	ds_read_b128 v[16:19], v64 offset:1024
	s_waitcnt lgkmcnt(0)
	v_mfma_f32_32x32x16_bf16 v[0:15], v[0:3], v[154:157], 0
	v_mfma_f32_32x32x16_bf16 v[0:15], v[16:19], v[130:133], v[0:15]
	ds_read_b128 v[16:19], v64 offset:2048
	ds_read_b128 v[20:23], v64 offset:3072
	s_waitcnt lgkmcnt(0)
	v_mfma_f32_32x32x16_bf16 v[0:15], v[16:19], v[134:137], v[0:15]
	v_mfma_f32_32x32x16_bf16 v[0:15], v[20:23], v[138:141], v[0:15]
	ds_read_b128 v[16:19], v64 offset:4096
	ds_read_b128 v[20:23], v64 offset:5120
	s_waitcnt lgkmcnt(0)
	v_mfma_f32_32x32x16_bf16 v[0:15], v[16:19], v[142:145], v[0:15]
	v_mfma_f32_32x32x16_bf16 v[0:15], v[20:23], v[146:149], v[0:15]
	ds_read_b128 v[16:19], v64 offset:6144
	ds_read_b128 v[20:23], v64 offset:7168
	s_waitcnt lgkmcnt(0)
	v_mfma_f32_32x32x16_bf16 v[0:15], v[16:19], v[150:153], v[0:15]
	ds_read_b128 v[16:19], v64 offset:8192
	ds_read_b128 v[174:177], v64 offset:9216
	v_mfma_f32_32x32x16_bf16 v[0:15], v[20:23], v[158:161], v[0:15]
	s_waitcnt lgkmcnt(0)
	v_mfma_f32_32x32x16_bf16 v[16:31], v[16:19], v[154:157], 0
	v_mfma_f32_32x32x16_bf16 v[16:31], v[174:177], v[130:133], v[16:31]
	ds_read_b128 v[174:177], v64 offset:10240
	ds_read_b128 v[178:181], v64 offset:11264
	s_waitcnt lgkmcnt(0)
	v_mfma_f32_32x32x16_bf16 v[16:31], v[174:177], v[134:137], v[16:31]
	v_mfma_f32_32x32x16_bf16 v[16:31], v[178:181], v[138:141], v[16:31]
	ds_read_b128 v[174:177], v64 offset:12288
	ds_read_b128 v[178:181], v64 offset:13312
	ds_read_b128 v[182:185], v64 offset:14336
	ds_read_b128 v[186:189], v64 offset:15360
	v_max3_f32 v64, v32, s78, v33
	v_max3_f32 v64, v64, v34, v35
	v_max3_f32 v64, v64, v36, v37
	v_max3_f32 v64, v64, v38, v39
	v_max3_f32 v64, v64, v40, v41
	v_max3_f32 v64, v64, v42, v43
	s_waitcnt lgkmcnt(0)
	v_mfma_f32_32x32x16_bf16 v[16:31], v[174:177], v[142:145], v[16:31]
	v_max3_f32 v64, v64, v44, v45
	v_max3_f32 v64, v64, v46, v47
	v_max3_f32 v64, v64, v48, v49
	v_max3_f32 v64, v64, v50, v51
	v_max3_f32 v64, v64, v52, v53
	v_max3_f32 v64, v64, v54, v55
	v_max3_f32 v64, v64, v56, v57
	v_mfma_f32_32x32x16_bf16 v[16:31], v[178:181], v[146:149], v[16:31]
	v_max3_f32 v64, v64, v58, v59
	v_max3_f32 v64, v64, v60, v61
	v_max3_f32 v64, v64, v62, v63
	v_fma_f32 v64, s6, v64, v172
	v_mov_b32_e32 v170, v64
	s_nop 1
	v_permlane32_swap_b32 v64, v170
	s_nop 1
	v_mfma_f32_32x32x16_bf16 v[16:31], v[182:185], v[150:153], v[16:31]
	v_max_f32_e32 v170, v64, v170
	v_add_f32_e32 v64, 0x41000000, v169
	v_cmp_gt_f32_e32 vcc, v170, v64
	s_nop 1
	v_cndmask_b32_e32 v170, v169, v170, vcc
	v_sub_f32_e32 v64, v169, v170
	v_exp_f32_e32 v64, v64
	s_nop 0
	v_cmp_neq_f32_e32 vcc, 1.0, v64
	v_mfma_f32_32x32x16_bf16 v[16:31], v[186:189], v[158:161], v[16:31]
	s_cbranch_vccz .LBB0_1221
	v_pk_mul_f32 v[128:129], v[128:129], v[64:65] op_sel_hi:[1,0]
	v_pk_mul_f32 v[126:127], v[126:127], v[64:65] op_sel_hi:[1,0]
	v_pk_mul_f32 v[124:125], v[124:125], v[64:65] op_sel_hi:[1,0]
	v_pk_mul_f32 v[122:123], v[122:123], v[64:65] op_sel_hi:[1,0]
	v_pk_mul_f32 v[120:121], v[120:121], v[64:65] op_sel_hi:[1,0]
	v_pk_mul_f32 v[118:119], v[118:119], v[64:65] op_sel_hi:[1,0]
	v_pk_mul_f32 v[116:117], v[116:117], v[64:65] op_sel_hi:[1,0]
	v_pk_mul_f32 v[114:115], v[114:115], v[64:65] op_sel_hi:[1,0]
	v_pk_mul_f32 v[112:113], v[112:113], v[64:65] op_sel_hi:[1,0]
	v_pk_mul_f32 v[110:111], v[110:111], v[64:65] op_sel_hi:[1,0]
	v_pk_mul_f32 v[108:109], v[108:109], v[64:65] op_sel_hi:[1,0]
	v_pk_mul_f32 v[106:107], v[106:107], v[64:65] op_sel_hi:[1,0]
	v_pk_mul_f32 v[104:105], v[104:105], v[64:65] op_sel_hi:[1,0]
	v_pk_mul_f32 v[102:103], v[102:103], v[64:65] op_sel_hi:[1,0]
	v_pk_mul_f32 v[100:101], v[100:101], v[64:65] op_sel_hi:[1,0]
	v_pk_mul_f32 v[98:99], v[98:99], v[64:65] op_sel_hi:[1,0]
	v_pk_mul_f32 v[96:97], v[96:97], v[64:65] op_sel_hi:[1,0]
	v_pk_mul_f32 v[94:95], v[94:95], v[64:65] op_sel_hi:[1,0]
	v_pk_mul_f32 v[92:93], v[92:93], v[64:65] op_sel_hi:[1,0]
	v_pk_mul_f32 v[90:91], v[90:91], v[64:65] op_sel_hi:[1,0]
	v_pk_mul_f32 v[88:89], v[88:89], v[64:65] op_sel_hi:[1,0]
	v_pk_mul_f32 v[86:87], v[86:87], v[64:65] op_sel_hi:[1,0]
	v_pk_mul_f32 v[84:85], v[84:85], v[64:65] op_sel_hi:[1,0]
	v_pk_mul_f32 v[82:83], v[82:83], v[64:65] op_sel_hi:[1,0]
	v_pk_mul_f32 v[80:81], v[80:81], v[64:65] op_sel_hi:[1,0]
	v_pk_mul_f32 v[78:79], v[78:79], v[64:65] op_sel_hi:[1,0]
	v_pk_mul_f32 v[76:77], v[76:77], v[64:65] op_sel_hi:[1,0]
	v_pk_mul_f32 v[74:75], v[74:75], v[64:65] op_sel_hi:[1,0]
	v_pk_mul_f32 v[72:73], v[72:73], v[64:65] op_sel_hi:[1,0]
	v_pk_mul_f32 v[70:71], v[70:71], v[64:65] op_sel_hi:[1,0]
	v_pk_mul_f32 v[68:69], v[68:69], v[64:65] op_sel_hi:[1,0]
	v_pk_mul_f32 v[66:67], v[66:67], v[64:65] op_sel_hi:[1,0]

; #define LAS __attribute__((address_space(3)))
; __device__ __forceinline__ f32x16 mfma32(bf16x8 a, bf16x8 b, f32x16 c) { return __builtin_amdgcn_mfma_f32_32x32x16_bf16(a, b, c, 0, 0, 0); }
; template <int MODE> ...
;     ...
;     { const LAS unsigned char* kp = lds + NSA_KB + bufn * 16384 + lane * 16;
; #pragma unroll
;       for (int kt = 0; kt < 2; ++kt) { sn[kt] = zero16();
; #pragma unroll
;           for (int ks = 0; ks < 8; ++ks) sn[kt] = mfma32(*(const LAS bf16x8*)(kp + kt * 8192 + ks * 1024), qf[ks], sn[kt]); } }
;     if (MODE == 1) {
; #pragma unroll
;         for (int kt = 0; kt < 2; ++kt)
; #pragma unroll
;             for (int r = 0; r < 16; ++r) s[kt][r] = (s[kt][r] > -1e29f) ? __builtin_amdgcn_exp2f(s[kt][r] - m_fin) * invl : 0.f;
;         LAS float* impa = (LAS float*)(lds + NSA_IMPA) + w * 8 * 66;
;         LAS float* impb = (LAS float*)(lds + NSA_IMPB) + w * 8 * 66;
; #pragma unroll
;         for (int kt = 0; kt < 2; ++kt)
; #pragma unroll
;             for (int q = 0; q < 4; ++q) {
;                 float A_ = s[kt][4 * q] + s[kt][4 * q + 1] + s[kt][4 * q + 2] + 0.5f * s[kt][4 * q + 3], B_ = 0.5f * s[kt][4 * q + 3];
;                 A_ += __shfl_xor(A_, 1); A_ += __shfl_xor(A_, 2); B_ += __shfl_xor(B_, 1); B_ += __shfl_xor(B_, 2);
;                 const int j = 8 * (2 * idx + kt) + 2 * q + hi;
;                 if (hd == 0) { impa[tl * 66 + j] = A_; impb[tl * 66 + j + 1] = B_; }
;             }
;     } else {
;         float tm = -3.0e38f;
; #pragma unroll
;         for (int kt = 0; kt < 2; ++kt)
; #pragma unroll
;             for (int r = 0; r < 16; r += 2) tm = fmaxf(fmaxf(tm, s[kt][r]), s[kt][r + 1]);
;         tm = tm * cs + offl;
;         tm = max_xor32(tm);
;         const float mn = fmaxf(mrun, tm), al = __builtin_amdgcn_exp2f(mrun - mn); float ps = 0.f;
;         const float om = offl - mn;
; #pragma unroll
;         for (int kt = 0; kt < 2; ++kt)
; #pragma unroll
;             for (int r = 0; r < 16; ++r) { const float p = __builtin_amdgcn_exp2f(s[kt][r] * cs + om); s[kt][r] = p; ps += p; }
;         lrun = lrun * al + ps; mrun = mn;
;         if (MODE != 0) {
;             if (__builtin_amdgcn_ballot_w64(al != 1.0f)) {
; #pragma unroll
;                 for (int dt = 0; dt < 4; ++dt) O[dt] = O[dt] * al;
;             }
;         }
.LBB0_1237:
	s_or_b64 exec, exec, s[10:11]
	s_lshl_b32 s0, s14, 14
	s_add_i32 s0, s0, 0
	v_lshlrev_b32_e32 v170, 4, v32
	v_add_u32_e32 v64, s0, v170
	ds_read_b128 v[32:35], v64
	ds_read_b128 v[48:51], v64 offset:1024
	s_waitcnt lgkmcnt(0)
	v_mfma_f32_32x32x16_bf16 v[32:47], v[32:35], v[154:157], 0
	v_mfma_f32_32x32x16_bf16 v[32:47], v[48:51], v[130:133], v[32:47]
	ds_read_b128 v[48:51], v64 offset:2048
	ds_read_b128 v[52:55], v64 offset:3072
	s_waitcnt lgkmcnt(0)
	v_mfma_f32_32x32x16_bf16 v[32:47], v[48:51], v[134:137], v[32:47]
	v_mfma_f32_32x32x16_bf16 v[32:47], v[52:55], v[138:141], v[32:47]
	ds_read_b128 v[48:51], v64 offset:4096
	ds_read_b128 v[52:55], v64 offset:5120
	s_waitcnt lgkmcnt(0)
	v_mfma_f32_32x32x16_bf16 v[32:47], v[48:51], v[142:145], v[32:47]
	v_mfma_f32_32x32x16_bf16 v[32:47], v[52:55], v[146:149], v[32:47]
	ds_read_b128 v[48:51], v64 offset:6144
	ds_read_b128 v[52:55], v64 offset:7168
	s_waitcnt lgkmcnt(0)
	v_mfma_f32_32x32x16_bf16 v[32:47], v[48:51], v[150:153], v[32:47]
	ds_read_b128 v[48:51], v64 offset:8192
	ds_read_b128 v[172:175], v64 offset:9216
	v_mfma_f32_32x32x16_bf16 v[32:47], v[52:55], v[158:161], v[32:47]
	s_waitcnt lgkmcnt(0)
	v_mfma_f32_32x32x16_bf16 v[48:63], v[48:51], v[154:157], 0
	v_mfma_f32_32x32x16_bf16 v[48:63], v[172:175], v[130:133], v[48:63]
	ds_read_b128 v[172:175], v64 offset:10240
	ds_read_b128 v[176:179], v64 offset:11264
	s_waitcnt lgkmcnt(0)
	v_mfma_f32_32x32x16_bf16 v[48:63], v[172:175], v[134:137], v[48:63]
	v_mfma_f32_32x32x16_bf16 v[48:63], v[176:179], v[138:141], v[48:63]
	ds_read_b128 v[172:175], v64 offset:12288
	ds_read_b128 v[176:179], v64 offset:13312
	ds_read_b128 v[180:183], v64 offset:14336
	ds_read_b128 v[184:187], v64 offset:15360
	v_max3_f32 v64, v0, s78, v1
	v_max3_f32 v64, v64, v2, v3
	v_max3_f32 v64, v64, v4, v5
	v_max3_f32 v64, v64, v6, v7
	v_max3_f32 v64, v64, v8, v9
	v_max3_f32 v64, v64, v10, v11
	s_waitcnt lgkmcnt(0)
	v_mfma_f32_32x32x16_bf16 v[48:63], v[172:175], v[142:145], v[48:63]
	v_max3_f32 v64, v64, v12, v13
	v_max3_f32 v64, v64, v14, v15
	v_max3_f32 v64, v64, v16, v17
	v_max3_f32 v64, v64, v18, v19
	v_max3_f32 v64, v64, v20, v21
	v_max3_f32 v64, v64, v22, v23
	v_max3_f32 v64, v64, v24, v25
	v_mfma_f32_32x32x16_bf16 v[48:63], v[176:179], v[146:149], v[48:63]
	v_max3_f32 v64, v64, v26, v27
	v_max3_f32 v64, v64, v28, v29
	v_max3_f32 v64, v64, v30, v31
	v_fma_f32 v64, v166, v64, v171
	v_mov_b32_e32 v167, v64
	s_nop 1
	v_permlane32_swap_b32 v64, v167
	s_nop 1
	v_mfma_f32_32x32x16_bf16 v[48:63], v[180:183], v[150:153], v[48:63]
	v_max_f32_e32 v167, v64, v167
	v_add_f32_e32 v64, 0x41000000, v169
	v_cmp_gt_f32_e32 vcc, v167, v64
	s_nop 1
	v_cndmask_b32_e32 v167, v169, v167, vcc
	v_sub_f32_e32 v64, v169, v167
	v_exp_f32_e32 v64, v64
	s_nop 0
	v_cmp_neq_f32_e32 vcc, 1.0, v64
	v_mfma_f32_32x32x16_bf16 v[48:63], v[184:187], v[158:161], v[48:63]
	s_cbranch_vccz .LBB0_1228
	v_pk_mul_f32 v[128:129], v[128:129], v[64:65] op_sel_hi:[1,0]
	v_pk_mul_f32 v[126:127], v[126:127], v[64:65] op_sel_hi:[1,0]
	v_pk_mul_f32 v[124:125], v[124:125], v[64:65] op_sel_hi:[1,0]
	v_pk_mul_f32 v[122:123], v[122:123], v[64:65] op_sel_hi:[1,0]
	v_pk_mul_f32 v[120:121], v[120:121], v[64:65] op_sel_hi:[1,0]
	v_pk_mul_f32 v[118:119], v[118:119], v[64:65] op_sel_hi:[1,0]
	v_pk_mul_f32 v[116:117], v[116:117], v[64:65] op_sel_hi:[1,0]
	v_pk_mul_f32 v[114:115], v[114:115], v[64:65] op_sel_hi:[1,0]
	v_pk_mul_f32 v[112:113], v[112:113], v[64:65] op_sel_hi:[1,0]
	v_pk_mul_f32 v[110:111], v[110:111], v[64:65] op_sel_hi:[1,0]
	v_pk_mul_f32 v[108:109], v[108:109], v[64:65] op_sel_hi:[1,0]
	v_pk_mul_f32 v[106:107], v[106:107], v[64:65] op_sel_hi:[1,0]
	v_pk_mul_f32 v[104:105], v[104:105], v[64:65] op_sel_hi:[1,0]
	v_pk_mul_f32 v[102:103], v[102:103], v[64:65] op_sel_hi:[1,0]
	v_pk_mul_f32 v[100:101], v[100:101], v[64:65] op_sel_hi:[1,0]
	v_pk_mul_f32 v[98:99], v[98:99], v[64:65] op_sel_hi:[1,0]
	v_pk_mul_f32 v[96:97], v[96:97], v[64:65] op_sel_hi:[1,0]
	v_pk_mul_f32 v[94:95], v[94:95], v[64:65] op_sel_hi:[1,0]
	v_pk_mul_f32 v[92:93], v[92:93], v[64:65] op_sel_hi:[1,0]
	v_pk_mul_f32 v[90:91], v[90:91], v[64:65] op_sel_hi:[1,0]
	v_pk_mul_f32 v[88:89], v[88:89], v[64:65] op_sel_hi:[1,0]
	v_pk_mul_f32 v[86:87], v[86:87], v[64:65] op_sel_hi:[1,0]
	v_pk_mul_f32 v[84:85], v[84:85], v[64:65] op_sel_hi:[1,0]
	v_pk_mul_f32 v[82:83], v[82:83], v[64:65] op_sel_hi:[1,0]
	v_pk_mul_f32 v[80:81], v[80:81], v[64:65] op_sel_hi:[1,0]
	v_pk_mul_f32 v[78:79], v[78:79], v[64:65] op_sel_hi:[1,0]
	v_pk_mul_f32 v[76:77], v[76:77], v[64:65] op_sel_hi:[1,0]
	v_pk_mul_f32 v[74:75], v[74:75], v[64:65] op_sel_hi:[1,0]
	v_pk_mul_f32 v[72:73], v[72:73], v[64:65] op_sel_hi:[1,0]
	v_pk_mul_f32 v[70:71], v[70:71], v[64:65] op_sel_hi:[1,0]
	v_pk_mul_f32 v[68:69], v[68:69], v[64:65] op_sel_hi:[1,0]
	v_pk_mul_f32 v[66:67], v[66:67], v[64:65] op_sel_hi:[1,0]
	s_branch .LBB0_1228
